# P2 deferred weight conversion: pulled batch size 64 -> 32 items (4 per wave) for a finer-grained post-GEMM tail
# speedup vs baseline: 1.0006x; 1.0006x over previous
.LBB0_196:
	s_or_b64 exec, exec, s[30:31]
	s_waitcnt lgkmcnt(0)
	s_waitcnt lgkmcnt(0)
	s_barrier
	ds_read_b32 v0, v142
	s_mov_b64 s[30:31], -1
	s_waitcnt lgkmcnt(0)
	s_barrier
	v_readfirstlane_b32 s28, v0
	s_cmpk_gt_i32 s28, 0x561
	s_cbranch_scc1 .LBB0_191
	s_lshl_b32 s38, s28, 5
	v_readlane_b32 s28, v252, 6
	s_add_i32 s28, s38, s28
	s_cmpk_lt_i32 s28, 0x2b00
	s_movk_i32 s29, 0x2b00
	s_cbranch_scc1 .LBB0_205
	s_cmpk_gt_u32 s28, 0x413f
	s_cbranch_scc0 .LBB0_206
	s_cmpk_gt_u32 s28, 0x443f
	s_cbranch_scc0 .LBB0_207
	s_cmpk_gt_u32 s28, 0x463f
	s_cbranch_scc0 .LBB0_208
	v_readlane_b32 s40, v252, 54
	v_readlane_b32 s50, v253, 0
	v_readlane_b32 s51, v253, 1
	s_cmpk_gt_u32 s28, 0x563f
	s_mov_b64 s[76:77], -1
	s_mov_b64 s[72:73], s[50:51]
	v_readlane_b32 s41, v252, 55
	v_readlane_b32 s42, v252, 56
	v_readlane_b32 s43, v252, 57
	v_readlane_b32 s44, v252, 58
	v_readlane_b32 s45, v252, 59
	v_readlane_b32 s46, v252, 60
	v_readlane_b32 s47, v252, 61
	v_readlane_b32 s48, v252, 62
	v_readlane_b32 s49, v252, 63
	v_readlane_b32 s52, v253, 2
	v_readlane_b32 s53, v253, 3
	v_readlane_b32 s54, v253, 4
	v_readlane_b32 s55, v253, 5
	s_cbranch_scc0 .LBB0_203
	s_add_i32 s36, s28, 0xffffa9c0
	s_mov_b64 s[30:31], 0
	s_mov_b64 s[72:73], s[20:21]

.LBB0_275:
	s_lshl_b32 s80, s41, 6
	v_add_u32_e32 v64, s80, v134
	v_ashrrev_i32_e32 v67, 31, v64
	v_mad_u64_u32 v[64:65], s[30:31], v64, s34, 0
	v_mov_b32_e32 v66, v65
	v_mad_u64_u32 v[66:67], s[30:31], v67, s34, v[66:67]
	v_mov_b32_e32 v65, v66
	v_lshl_add_u64 v[64:65], v[64:65], 2, s[82:83]
	s_ashr_i32 s93, s92, 31
	v_lshl_add_u64 v[64:65], s[92:93], 2, v[64:65]
	v_lshl_add_u64 v[64:65], v[64:65], 0, v[128:129]
	s_lshl_b64 s[30:31], s[34:35], 2
	v_lshl_add_u64 v[66:67], v[64:65], 0, s[30:31]
	s_mul_i32 s34, s34, 28
	global_load_dwordx4 v[96:99], v[64:65], off nt
	global_load_dwordx4 v[104:107], v[66:67], off nt
	v_lshl_add_u64 v[64:65], v[66:67], 0, s[34:35]
	v_lshl_add_u64 v[66:67], v[64:65], 0, s[30:31]
	global_load_dwordx4 v[116:119], v[64:65], off nt
	global_load_dwordx4 v[124:127], v[66:67], off nt
	v_lshl_add_u64 v[64:65], v[66:67], 0, s[34:35]
	v_lshl_add_u64 v[66:67], v[64:65], 0, s[30:31]
	global_load_dwordx4 v[108:111], v[64:65], off nt
	global_load_dwordx4 v[120:123], v[66:67], off nt
	v_lshl_add_u64 v[64:65], v[66:67], 0, s[34:35]
	v_lshl_add_u64 v[66:67], v[64:65], 0, s[30:31]
	global_load_dwordx4 v[100:103], v[64:65], off nt
	global_load_dwordx4 v[112:115], v[66:67], off nt
	v_lshl_add_u64 v[64:65], v[66:67], 0, s[34:35]
	global_load_dwordx4 v[84:87], v[64:65], off nt
	v_lshl_add_u64 v[64:65], v[64:65], 0, s[30:31]
	global_load_dwordx4 v[92:95], v[64:65], off nt
	v_lshl_add_u64 v[64:65], v[64:65], 0, s[34:35]
	global_load_dwordx4 v[76:79], v[64:65], off nt
	v_lshl_add_u64 v[64:65], v[64:65], 0, s[30:31]
	global_load_dwordx4 v[88:91], v[64:65], off nt
	v_lshl_add_u64 v[64:65], v[64:65], 0, s[34:35]
	global_load_dwordx4 v[68:71], v[64:65], off nt
	v_lshl_add_u64 v[64:65], v[64:65], 0, s[30:31]
	v_lshl_add_u64 v[72:73], v[64:65], 0, s[34:35]
	global_load_dwordx4 v[80:83], v[64:65], off nt
	s_nop 0
	global_load_dwordx4 v[64:67], v[72:73], off nt
	v_lshl_add_u64 v[72:73], v[72:73], 0, s[30:31]
	global_load_dwordx4 v[72:75], v[72:73], off nt
	s_waitcnt vmcnt(30)
	v_cvt_pk_bf16_f32 v132, v0, v4
	v_cvt_pk_bf16_f32 v133, v1, v5
	ds_write2_b32 v143, v132, v133 offset1:32
	v_cvt_pk_bf16_f32 v132, v2, v6
	v_cvt_pk_bf16_f32 v133, v3, v7
	ds_write2_b32 v143, v132, v133 offset0:64 offset1:96
	s_waitcnt vmcnt(28)
	v_cvt_pk_bf16_f32 v132, v8, v12
	v_cvt_pk_bf16_f32 v133, v9, v13
	ds_write2_b32 v144, v132, v133 offset1:32
	v_cvt_pk_bf16_f32 v132, v10, v14
	v_cvt_pk_bf16_f32 v133, v11, v15
	ds_write2_b32 v144, v132, v133 offset0:64 offset1:96
	s_waitcnt vmcnt(26)
	v_cvt_pk_bf16_f32 v132, v16, v20
	v_cvt_pk_bf16_f32 v133, v17, v21
	ds_write2_b32 v145, v132, v133 offset1:32
	v_cvt_pk_bf16_f32 v132, v18, v22
	v_cvt_pk_bf16_f32 v133, v19, v23
	ds_write2_b32 v145, v132, v133 offset0:64 offset1:96
	s_waitcnt vmcnt(24)
	v_cvt_pk_bf16_f32 v132, v24, v28
	v_cvt_pk_bf16_f32 v133, v25, v29
	ds_write2_b32 v146, v132, v133 offset1:32
	v_cvt_pk_bf16_f32 v132, v26, v30
	v_cvt_pk_bf16_f32 v133, v27, v31
	ds_write2_b32 v146, v132, v133 offset0:64 offset1:96
	s_waitcnt vmcnt(22)
	v_cvt_pk_bf16_f32 v132, v32, v36
	v_cvt_pk_bf16_f32 v133, v33, v37
	ds_write2_b32 v147, v132, v133 offset1:32
	v_cvt_pk_bf16_f32 v132, v34, v38
	v_cvt_pk_bf16_f32 v133, v35, v39
	ds_write2_b32 v147, v132, v133 offset0:64 offset1:96
	s_waitcnt vmcnt(20)
	v_cvt_pk_bf16_f32 v132, v40, v44
	v_cvt_pk_bf16_f32 v133, v41, v45
	ds_write2_b32 v148, v132, v133 offset1:32
	v_cvt_pk_bf16_f32 v132, v42, v46
	v_cvt_pk_bf16_f32 v133, v43, v47
	ds_write2_b32 v148, v132, v133 offset0:64 offset1:96
	s_waitcnt vmcnt(18)
	v_cvt_pk_bf16_f32 v132, v48, v52
	v_cvt_pk_bf16_f32 v133, v49, v53
	ds_write2_b32 v149, v132, v133 offset1:32
	v_cvt_pk_bf16_f32 v132, v50, v54
	v_cvt_pk_bf16_f32 v133, v51, v55
	ds_write2_b32 v149, v132, v133 offset0:64 offset1:96
	s_waitcnt vmcnt(16)
	v_cvt_pk_bf16_f32 v132, v56, v60
	v_cvt_pk_bf16_f32 v133, v57, v61
	s_sub_i32 s30, s37, 32
	ds_write2_b32 v150, v132, v133 offset1:32
	v_cvt_pk_bf16_f32 v132, v58, v62
	v_cvt_pk_bf16_f32 v133, v59, v63
	v_mov_b32_e32 v159, s30
	v_mov_b32_e32 v168, s36
	ds_write2_b32 v150, v132, v133 offset0:64 offset1:96
	v_cndmask_b32_e64 v132, v159, v168, s[2:3]
	v_add_u32_e32 v132, v132, v131
	s_waitcnt lgkmcnt(0)
	v_ashrrev_i32_e32 v165, 31, v132
	v_mad_u64_u32 v[132:133], s[30:31], v132, s29, 0
	v_mov_b32_e32 v164, v133
	ds_read_b128 v[160:163], v151
	v_mad_u64_u32 v[164:165], s[30:31], v165, s29, v[164:165]
	v_mov_b32_e32 v133, v164
	s_ashr_i32 s79, s78, 31
	v_lshl_add_u64 v[132:133], v[132:133], 1, s[76:77]
	s_lshl_b64 s[30:31], s[78:79], 1
	v_lshl_add_u64 v[164:165], v[132:133], 0, s[30:31]
	v_lshlrev_b32_e32 v132, 1, v130
	v_mov_b32_e32 v133, v129
	v_lshl_add_u64 v[164:165], v[164:165], 0, v[132:133]
	s_waitcnt lgkmcnt(0)
	global_store_dwordx4 v[164:165], v[160:163], off
	v_cndmask_b32_e64 v164, v159, v168, s[4:5]
	v_add_u32_e32 v164, v164, v135
	v_ashrrev_i32_e32 v167, 31, v164
	v_mad_u64_u32 v[164:165], s[42:43], v164, s29, 0
	v_mov_b32_e32 v166, v165
	ds_read_b128 v[160:163], v152
	v_mad_u64_u32 v[166:167], s[42:43], v167, s29, v[166:167]
	v_mov_b32_e32 v165, v166
	v_lshl_add_u64 v[164:165], v[164:165], 1, s[76:77]
	v_lshl_add_u64 v[164:165], v[164:165], 0, s[30:31]
	v_lshl_add_u64 v[164:165], v[164:165], 0, v[132:133]
	s_waitcnt lgkmcnt(0)
	global_store_dwordx4 v[164:165], v[160:163], off
	v_cndmask_b32_e64 v164, v159, v168, s[6:7]
	v_add_u32_e32 v164, v164, v136
	v_ashrrev_i32_e32 v167, 31, v164
	v_mad_u64_u32 v[164:165], s[42:43], v164, s29, 0
	v_mov_b32_e32 v166, v165
	ds_read_b128 v[160:163], v153
	v_mad_u64_u32 v[166:167], s[42:43], v167, s29, v[166:167]
	v_mov_b32_e32 v165, v166
	v_lshl_add_u64 v[164:165], v[164:165], 1, s[76:77]
	v_lshl_add_u64 v[164:165], v[164:165], 0, s[30:31]
	v_lshl_add_u64 v[164:165], v[164:165], 0, v[132:133]
	s_waitcnt lgkmcnt(0)
	global_store_dwordx4 v[164:165], v[160:163], off
	v_cndmask_b32_e64 v164, v159, v168, s[8:9]
	v_add_u32_e32 v164, v164, v137
	v_ashrrev_i32_e32 v167, 31, v164
	v_mad_u64_u32 v[164:165], s[42:43], v164, s29, 0
	v_mov_b32_e32 v166, v165
	ds_read_b128 v[160:163], v154
	v_mad_u64_u32 v[166:167], s[42:43], v167, s29, v[166:167]
	v_mov_b32_e32 v165, v166
	v_lshl_add_u64 v[164:165], v[164:165], 1, s[76:77]
	v_lshl_add_u64 v[164:165], v[164:165], 0, s[30:31]
	v_lshl_add_u64 v[164:165], v[164:165], 0, v[132:133]
	s_waitcnt lgkmcnt(0)
	global_store_dwordx4 v[164:165], v[160:163], off
	v_cndmask_b32_e64 v164, v159, v168, s[10:11]
	v_add_u32_e32 v164, v164, v138
	v_ashrrev_i32_e32 v167, 31, v164
	v_mad_u64_u32 v[164:165], s[42:43], v164, s29, 0
	v_mov_b32_e32 v166, v165
	ds_read_b128 v[160:163], v155
	v_mad_u64_u32 v[166:167], s[42:43], v167, s29, v[166:167]
	v_mov_b32_e32 v165, v166
	v_lshl_add_u64 v[164:165], v[164:165], 1, s[76:77]
	v_lshl_add_u64 v[164:165], v[164:165], 0, s[30:31]
	v_lshl_add_u64 v[164:165], v[164:165], 0, v[132:133]
	s_waitcnt lgkmcnt(0)
	global_store_dwordx4 v[164:165], v[160:163], off
	v_cndmask_b32_e64 v164, v159, v168, s[12:13]
	v_add_u32_e32 v164, v164, v139
	v_ashrrev_i32_e32 v167, 31, v164
	v_mad_u64_u32 v[164:165], s[42:43], v164, s29, 0
	v_mov_b32_e32 v166, v165
	ds_read_b128 v[160:163], v156
	v_mad_u64_u32 v[166:167], s[42:43], v167, s29, v[166:167]
	v_mov_b32_e32 v165, v166
	v_lshl_add_u64 v[164:165], v[164:165], 1, s[76:77]
	v_lshl_add_u64 v[164:165], v[164:165], 0, s[30:31]
	v_lshl_add_u64 v[164:165], v[164:165], 0, v[132:133]
	s_waitcnt lgkmcnt(0)
	global_store_dwordx4 v[164:165], v[160:163], off
	v_cndmask_b32_e64 v164, v159, v168, s[14:15]
	v_add_u32_e32 v164, v164, v140
	v_ashrrev_i32_e32 v167, 31, v164
	v_mad_u64_u32 v[164:165], s[42:43], v164, s29, 0
	v_mov_b32_e32 v166, v165
	ds_read_b128 v[160:163], v157
	v_mad_u64_u32 v[166:167], s[42:43], v167, s29, v[166:167]
	v_mov_b32_e32 v165, v166
	v_lshl_add_u64 v[164:165], v[164:165], 1, s[76:77]
	v_lshl_add_u64 v[164:165], v[164:165], 0, s[30:31]
	v_cndmask_b32_e64 v159, v159, v168, s[16:17]
	v_lshl_add_u64 v[164:165], v[164:165], 0, v[132:133]
	v_add_u32_e32 v159, v159, v141
	s_waitcnt lgkmcnt(0)
	global_store_dwordx4 v[164:165], v[160:163], off
	v_mad_u64_u32 v[164:165], s[42:43], v159, s29, 0
	v_ashrrev_i32_e32 v167, 31, v159
	v_mov_b32_e32 v166, v165
	ds_read_b128 v[160:163], v158
	v_mad_u64_u32 v[166:167], s[42:43], v167, s29, v[166:167]
	v_mov_b32_e32 v165, v166
	v_lshl_add_u64 v[164:165], v[164:165], 1, s[76:77]
	v_lshl_add_u64 v[164:165], v[164:165], 0, s[30:31]
	v_lshl_add_u64 v[164:165], v[164:165], 0, v[132:133]
	s_waitcnt lgkmcnt(0)
	global_store_dwordx4 v[164:165], v[160:163], off
	s_waitcnt lgkmcnt(0)
	s_add_i32 s41, s40, 2
	s_cmp_gt_u32 s40, 1
	s_cselect_b64 s[82:83], -1, 0
	s_and_b64 vcc, exec, s[82:83]
	s_cbranch_vccnz .LBB0_236
	s_lshl_b32 s29, s41, 3
	s_add_i32 s36, s29, s28
	s_cmpk_lt_i32 s53, 0x2b00
	s_movk_i32 s29, 0x2b00
	s_cbranch_scc1 .LBB0_284
	s_cmpk_gt_u32 s53, 0x413f
	s_cbranch_scc0 .LBB0_285
	s_cmpk_gt_u32 s53, 0x443f
	s_cbranch_scc0 .LBB0_286
	s_cmpk_gt_u32 s53, 0x463f
	s_cbranch_scc0 .LBB0_287
	v_readlane_b32 s56, v252, 54
	v_readlane_b32 s66, v253, 0
	v_readlane_b32 s67, v253, 1
	s_cmpk_gt_u32 s53, 0x563f
	s_mov_b64 s[78:79], -1
	s_mov_b64 s[86:87], s[66:67]
	s_mov_b64 s[30:31], -1
	v_readlane_b32 s57, v252, 55
	v_readlane_b32 s58, v252, 56
	v_readlane_b32 s59, v252, 57
	v_readlane_b32 s60, v252, 58
	v_readlane_b32 s61, v252, 59
	v_readlane_b32 s62, v252, 60
	v_readlane_b32 s63, v252, 61
	v_readlane_b32 s64, v252, 62
	v_readlane_b32 s65, v252, 63
	v_readlane_b32 s68, v253, 2
	v_readlane_b32 s69, v253, 3
	v_readlane_b32 s70, v253, 4
	v_readlane_b32 s71, v253, 5
	s_cbranch_scc0 .LBB0_282
	s_add_i32 s37, s53, 0xffffa9c0
	s_mov_b64 s[30:31], 0
	s_mov_b64 s[86:87], s[20:21]
